# sample-row mini GEMMs and P7 fix-up items: operand loads issued in line groups (4 consecutive k-steps of one operand back to back) so the 32-byte pieces of a 128-byte line reuse L1
# speedup vs baseline: 1.0072x; 1.0072x over previous
; __device__ __forceinline__ unsigned f2bf(float f) { unsigned u = __float_as_uint(f); return (u + 0x7fffu + ((u >> 16) & 1u)) >> 16; }
; template <int MODE>
; __device__ __forceinline__ void mini_gemm(LAS unsigned char* lds, const bf16_t* A, const bf16_t* Bt, int K, int N, bf16_t* O, int ldc, const float* rstd, float* sumsq, int bx, int G, int tid, int wave, int lane) {
;     ...
;     for (int tile = bx; tile < ntiles; tile += G) {
;         const int m0 = (tile / ntn) * 32, n0 = (tile % ntn) * 32;
;         const bf16_t* ap = A + (size_t)(m0 + r) * K + wave * kw + 8 * hf; const bf16_t* bp = Bt + (size_t)(n0 + r) * K + wave * kw + 8 * hf;
;         f32x16 acc; for (int i = 0; i < 16; ++i) acc[i] = 0.f;
;         for (int k = 0; k < kw; k += 16) { const bf16x8 af = *(const bf16x8*)(ap + k), bf = *(const bf16x8*)(bp + k); acc = __builtin_amdgcn_mfma_f32_32x32x16_bf16(af, bf, acc, 0, 0, 0); }
;         __syncthreads();
; #pragma unroll
;         for (int i = 0; i < 16; ++i) red[(wave * 16 + i) * 64 + lane] = acc[i];
;         __syncthreads();
; #pragma unroll
;         for (int h2 = 0; h2 < 2; ++h2) {
;             const int e = tid + h2 * 512, i = e >> 6, ln = e & 63;
;             float v = 0.f;
; #pragma unroll
;             for (int w = 0; w < 8; ++w) v += red[(w * 16 + i) * 64 + ln];
;             const int row = m0 + (i & 3) + 8 * (i >> 2) + 4 * (ln >> 5), col = n0 + (ln & 31);
;             if (MODE == 0) { O[(size_t)row * ldc + col] = (bf16_t)f2bf(v * rstd[row]); }
.LBB0_169:
	s_ashr_i32 s11, s10, 31
	s_lshr_b32 s11, s11, 26
	s_add_i32 s11, s10, s11
	s_ashr_i32 s11, s11, 6
	s_lshl_b32 s12, s11, 5
	s_lshl_b32 s11, s11, 11
	v_or_b32_e32 v0, s12, v20
	v_subrev_u32_e32 v48, s11, v26
	v_ashrrev_i32_e32 v1, 31, v0
	v_ashrrev_i32_e32 v49, 31, v48
	v_lshlrev_b64 v[0:1], 11, v[0:1]
	v_lshlrev_b64 v[2:3], 11, v[48:49]
	v_lshl_add_u64 v[50:51], v[16:17], 0, v[0:1]
	v_lshl_add_u64 v[52:53], v[18:19], 0, v[2:3]
	s_add_i32 s10, s10, s38
	v_add_u32_e32 v26, s8, v26
	s_cmpk_lt_i32 s10, 0x200
	v_or_b32_e32 v41, s12, v21
	v_or_b32_e32 v40, v41, v23
	v_add_u32_e32 v42, v41, v25
	v_ashrrev_i32_e32 v41, 31, v40
	v_ashrrev_i32_e32 v43, 31, v42
	v_lshl_add_u64 v[32:33], v[40:41], 2, s[6:7]
	v_lshl_add_u64 v[34:35], v[42:43], 2, s[6:7]
	global_load_dwordx4 v[100:103], v[50:51], off
	global_load_dwordx4 v[104:107], v[50:51], off offset:32
	global_load_dwordx4 v[108:111], v[50:51], off offset:64
	global_load_dwordx4 v[112:115], v[50:51], off offset:96
	global_load_dwordx4 v[132:135], v[52:53], off
	global_load_dwordx4 v[136:139], v[52:53], off offset:32
	global_load_dwordx4 v[140:143], v[52:53], off offset:64
	global_load_dwordx4 v[144:147], v[52:53], off offset:96
	global_load_dwordx4 v[116:119], v[50:51], off offset:128
	global_load_dwordx4 v[120:123], v[50:51], off offset:160
	global_load_dwordx4 v[124:127], v[50:51], off offset:192
	global_load_dwordx4 v[128:131], v[50:51], off offset:224
	global_load_dwordx4 v[148:151], v[52:53], off offset:128
	global_load_dwordx4 v[152:155], v[52:53], off offset:160
	global_load_dwordx4 v[156:159], v[52:53], off offset:192
	global_load_dwordx4 v[160:163], v[52:53], off offset:224
	s_waitcnt vmcnt(11)
	v_mfma_f32_32x32x16_bf16 v[0:15], v[100:103], v[132:135], 0
	s_waitcnt vmcnt(10)
	v_mfma_f32_32x32x16_bf16 v[0:15], v[104:107], v[136:139], v[0:15]
	s_waitcnt vmcnt(9)
	v_mfma_f32_32x32x16_bf16 v[0:15], v[108:111], v[140:143], v[0:15]
	s_waitcnt vmcnt(8)
	v_mfma_f32_32x32x16_bf16 v[0:15], v[112:115], v[144:147], v[0:15]
	s_waitcnt vmcnt(3)
	v_mfma_f32_32x32x16_bf16 v[0:15], v[116:119], v[148:151], v[0:15]
	s_waitcnt vmcnt(2)
	v_mfma_f32_32x32x16_bf16 v[0:15], v[120:123], v[152:155], v[0:15]
	s_barrier
	s_waitcnt vmcnt(1)
	v_mfma_f32_32x32x16_bf16 v[0:15], v[124:127], v[156:159], v[0:15]
	s_waitcnt vmcnt(0)
	v_mfma_f32_32x32x16_bf16 v[0:15], v[128:131], v[160:163], v[0:15]
	s_nop 11
	ds_write2st64_b32 v27, v0, v1 offset1:1
	ds_write2st64_b32 v27, v2, v3 offset0:2 offset1:3
	ds_write2st64_b32 v27, v4, v5 offset0:4 offset1:5
	ds_write2st64_b32 v27, v6, v7 offset0:6 offset1:7
	ds_write2st64_b32 v27, v8, v9 offset0:8 offset1:9
	ds_write2st64_b32 v27, v10, v11 offset0:10 offset1:11
	ds_write2st64_b32 v27, v12, v13 offset0:12 offset1:13
	ds_write2st64_b32 v27, v14, v15 offset0:14 offset1:15
	s_waitcnt lgkmcnt(0)
	s_barrier
	global_load_dword v32, v[32:33], off
	s_nop 0
	global_load_dword v33, v[34:35], off
	v_lshl_add_u64 v[0:1], v[48:49], 1, s[2:3]
	v_lshlrev_b64 v[2:3], 12, v[40:41]
	v_lshlrev_b64 v[4:5], 12, v[42:43]
	v_lshl_add_u64 v[2:3], v[0:1], 0, v[2:3]
	v_lshl_add_u64 v[0:1], v[0:1], 0, v[4:5]
	ds_read2st64_b32 v[4:5], v22 offset1:16
	ds_read2st64_b32 v[6:7], v22 offset0:32 offset1:48
	ds_read2st64_b32 v[8:9], v22 offset0:64 offset1:80
	ds_read2st64_b32 v[10:11], v22 offset0:96 offset1:112
	ds_read2st64_b32 v[12:13], v24 offset1:16
	ds_read2st64_b32 v[14:15], v24 offset0:32 offset1:48
	ds_read2st64_b32 v[28:29], v24 offset0:64 offset1:80
	ds_read2st64_b32 v[30:31], v24 offset0:96 offset1:112
	s_waitcnt lgkmcnt(7)
	v_add_f32_e32 v4, 0, v4
	s_waitcnt lgkmcnt(3)
	v_add_f32_e32 v12, 0, v12
	v_add_f32_e32 v4, v4, v5
	v_add_f32_e32 v5, v12, v13
	v_add_f32_e32 v4, v4, v6
	s_waitcnt lgkmcnt(2)
	v_add_f32_e32 v5, v5, v14
	v_add_f32_e32 v4, v4, v7
	v_add_f32_e32 v5, v5, v15
	v_add_f32_e32 v4, v4, v8
	s_waitcnt lgkmcnt(1)
	v_add_f32_e32 v5, v5, v28
	v_add_f32_e32 v4, v4, v9
	v_add_f32_e32 v5, v5, v29
	v_add_f32_e32 v4, v4, v10
	s_waitcnt lgkmcnt(0)
	v_add_f32_e32 v5, v5, v30
	v_add_f32_e32 v4, v4, v11
	v_add_f32_e32 v5, v5, v31
	s_waitcnt vmcnt(1)
	v_mul_f32_e32 v4, v4, v32
	s_waitcnt vmcnt(0)
	v_mul_f32_e32 v5, v5, v33
	v_bfe_u32 v6, v4, 16, 1
	v_bfe_u32 v7, v5, 16, 1
	v_add3_u32 v4, v4, v6, s9
	v_add3_u32 v5, v5, v7, s9
	global_store_short_d16_hi v[2:3], v4, off
	global_store_short_d16_hi v[0:1], v5, off
	s_cbranch_scc1 .LBB0_169

; __device__ __forceinline__ unsigned f2bf(float f) { unsigned u = __float_as_uint(f); return (u + 0x7fffu + ((u >> 16) & 1u)) >> 16; }
; template <int MODE>
; __device__ __forceinline__ void mini_gemm(LAS unsigned char* lds, const bf16_t* A, const bf16_t* Bt, int K, int N, bf16_t* O, int ldc, const float* rstd, float* sumsq, int bx, int G, int tid, int wave, int lane) {
;     ...
;     for (int tile = bx; tile < ntiles; tile += G) {
;         const int m0 = (tile / ntn) * 32, n0 = (tile % ntn) * 32;
;         const bf16_t* ap = A + (size_t)(m0 + r) * K + wave * kw + 8 * hf; const bf16_t* bp = Bt + (size_t)(n0 + r) * K + wave * kw + 8 * hf;
;         f32x16 acc; for (int i = 0; i < 16; ++i) acc[i] = 0.f;
;         for (int k = 0; k < kw; k += 16) { const bf16x8 af = *(const bf16x8*)(ap + k), bf = *(const bf16x8*)(bp + k); acc = __builtin_amdgcn_mfma_f32_32x32x16_bf16(af, bf, acc, 0, 0, 0); }
;         __syncthreads();
; #pragma unroll
;         for (int i = 0; i < 16; ++i) red[(wave * 16 + i) * 64 + lane] = acc[i];
;         __syncthreads();
; #pragma unroll
;         for (int h2 = 0; h2 < 2; ++h2) {
;             const int e = tid + h2 * 512, i = e >> 6, ln = e & 63;
;             float v = 0.f;
; #pragma unroll
;             for (int w = 0; w < 8; ++w) v += red[(w * 16 + i) * 64 + ln];
;             const int row = m0 + (i & 3) + 8 * (i >> 2) + 4 * (ln >> 5), col = n0 + (ln & 31);
;             if (MODE == 0) { O[(size_t)row * ldc + col] = (bf16_t)f2bf(v * rstd[row]); }
;             else { O[(size_t)row * ldc + col] = (bf16_t)f2bf(v); float ss = v * v;
; #pragma unroll
;                 for (int o = 1; o < 32; o <<= 1) ss += __shfl_xor(ss, o);
;                 if ((ln & 31) == 0) atomicAdd(sumsq + row, ss); }
.LBB0_990:
	s_ashr_i32 s0, s10, 31
	s_lshr_b32 s0, s0, 27
	s_add_i32 s0, s10, s0
	s_and_b32 s1, s0, 0xffffffe0
	v_or_b32_e32 v0, s1, v20
	v_ashrrev_i32_e32 v1, 31, v0
	v_lshlrev_b64 v[0:1], 11, v[0:1]
	v_lshl_add_u64 v[56:57], v[16:17], 0, v[0:1]
	s_lshl_b32 s0, s0, 5
	s_and_b32 s0, s0, 0xfffffc00
	v_subrev_u32_e32 v54, s0, v31
	v_ashrrev_i32_e32 v55, 31, v54
	s_waitcnt lgkmcnt(0)
	v_lshlrev_b64 v[4:5], 11, v[54:55]
	v_lshl_add_u64 v[58:59], v[18:19], 0, v[4:5]
	global_load_dwordx4 v[100:103], v[56:57], off
	global_load_dwordx4 v[104:107], v[56:57], off offset:32
	global_load_dwordx4 v[108:111], v[56:57], off offset:64
	global_load_dwordx4 v[112:115], v[56:57], off offset:96
	global_load_dwordx4 v[132:135], v[58:59], off
	global_load_dwordx4 v[136:139], v[58:59], off offset:32
	global_load_dwordx4 v[140:143], v[58:59], off offset:64
	global_load_dwordx4 v[144:147], v[58:59], off offset:96
	global_load_dwordx4 v[116:119], v[56:57], off offset:128
	global_load_dwordx4 v[120:123], v[56:57], off offset:160
	global_load_dwordx4 v[124:127], v[56:57], off offset:192
	global_load_dwordx4 v[128:131], v[56:57], off offset:224
	global_load_dwordx4 v[148:151], v[58:59], off offset:128
	global_load_dwordx4 v[152:155], v[58:59], off offset:160
	global_load_dwordx4 v[156:159], v[58:59], off offset:192
	global_load_dwordx4 v[160:163], v[58:59], off offset:224
	s_waitcnt vmcnt(11)
	v_mfma_f32_32x32x16_bf16 v[0:15], v[100:103], v[132:135], 0
	s_waitcnt vmcnt(10)
	v_mfma_f32_32x32x16_bf16 v[0:15], v[104:107], v[136:139], v[0:15]
	s_waitcnt vmcnt(9)
	v_mfma_f32_32x32x16_bf16 v[0:15], v[108:111], v[140:143], v[0:15]
	s_waitcnt vmcnt(8)
	v_mfma_f32_32x32x16_bf16 v[0:15], v[112:115], v[144:147], v[0:15]
	s_waitcnt vmcnt(3)
	v_mfma_f32_32x32x16_bf16 v[0:15], v[116:119], v[148:151], v[0:15]
	s_waitcnt vmcnt(2)
	v_mfma_f32_32x32x16_bf16 v[0:15], v[120:123], v[152:155], v[0:15]
	s_barrier
	s_waitcnt vmcnt(1)
	v_mfma_f32_32x32x16_bf16 v[0:15], v[124:127], v[156:159], v[0:15]
	s_waitcnt vmcnt(0)
	v_mfma_f32_32x32x16_bf16 v[0:15], v[128:131], v[160:163], v[0:15]
	s_nop 11
	ds_write2st64_b32 v32, v0, v1 offset1:1
	ds_write2st64_b32 v32, v2, v3 offset0:2 offset1:3
	ds_write2st64_b32 v32, v4, v5 offset0:4 offset1:5
	ds_write2st64_b32 v32, v6, v7 offset0:6 offset1:7
	ds_write2st64_b32 v32, v8, v9 offset0:8 offset1:9
	ds_write2st64_b32 v32, v10, v11 offset0:10 offset1:11
	ds_write2st64_b32 v32, v12, v13 offset0:12 offset1:13
	ds_write2st64_b32 v32, v14, v15 offset0:14 offset1:15
	s_waitcnt lgkmcnt(0)
	s_barrier
	ds_read2st64_b32 v[0:1], v22 offset1:16
	ds_read2st64_b32 v[2:3], v22 offset0:32 offset1:48
	ds_read2st64_b32 v[4:5], v22 offset0:64 offset1:80
	s_waitcnt lgkmcnt(2)
	v_add_f32_e32 v0, 0, v0
	v_add_f32_e32 v6, v0, v1
	ds_read2st64_b32 v[0:1], v22 offset0:96 offset1:112
	s_waitcnt lgkmcnt(2)
	v_add_f32_e32 v2, v6, v2
	v_add_f32_e32 v2, v2, v3
	s_waitcnt lgkmcnt(1)
	v_add_f32_e32 v2, v2, v4
	v_add_f32_e32 v2, v2, v5
	s_waitcnt lgkmcnt(0)
	v_add_f32_e32 v0, v2, v0
	v_add_f32_e32 v3, v0, v1
	v_mul_f32_e32 v0, v3, v3
	ds_bpermute_b32 v0, v24, v0
	v_or_b32_e32 v4, s1, v21
	v_or_b32_e32 v2, v4, v23
	v_bfe_u32 v7, v3, 16, 1
	v_add3_u32 v7, v3, v7, s9
	s_waitcnt lgkmcnt(0)
	v_fmac_f32_e32 v0, v3, v3
	ds_bpermute_b32 v1, v25, v0
	v_ashrrev_i32_e32 v3, 31, v2
	v_lshlrev_b64 v[8:9], 11, v[2:3]
	s_waitcnt lgkmcnt(0)
	v_add_f32_e32 v0, v0, v1
	ds_bpermute_b32 v1, v26, v0
	s_waitcnt lgkmcnt(0)
	v_add_f32_e32 v5, v0, v1
	ds_bpermute_b32 v6, v27, v5
	v_lshl_add_u64 v[0:1], v[54:55], 1, s[2:3]
	v_lshl_add_u64 v[8:9], v[0:1], 0, v[8:9]
	global_store_short_d16_hi v[8:9], v7, off
	s_waitcnt lgkmcnt(0)
	v_add_f32_e32 v5, v5, v6
	ds_bpermute_b32 v6, v28, v5
	s_and_saveexec_b64 s[0:1], vcc
	s_cbranch_execz .LBB0_992
	v_lshl_add_u64 v[2:3], v[2:3], 2, s[6:7]
	s_waitcnt lgkmcnt(0)
	v_add_f32_e32 v5, v5, v6
	global_atomic_add_f32 v[2:3], v5, off

; __device__ __forceinline__ void up_fixup(const Args& a, LAS unsigned char* lds, int bx, int G, int tid, int wave, int lane) {
;     ...
;     for (int item = bx; item < 176; item += G) {
;         const int mt = item / 88, cp = item % 88, pn = cp >> 2, sub = cp & 3;
;         const bf16_t* ap = hb + (size_t)fix_row(mt * 32 + r) * DM + wave * 128 + 8 * hf;
;         const bf16_t* bg = W + (size_t)(256 * pn + 32 * sub + r) * DM + wave * 128 + 8 * hf; const bf16_t* bv = bg + (size_t)128 * DM;
;         f32x16 ag, av; for (int i = 0; i < 16; ++i) { ag[i] = 0.f; av[i] = 0.f; }
; #pragma unroll
;         for (int k = 0; k < 128; k += 16) { const bf16x8 af = *(const bf16x8*)(ap + k); ag = __builtin_amdgcn_mfma_f32_32x32x16_bf16(af, *(const bf16x8*)(bg + k), ag, 0, 0, 0); av = __builtin_amdgcn_mfma_f32_32x32x16_bf16(af, *(const bf16x8*)(bv + k), av, 0, 0, 0); }
;         __syncthreads();
.LBB0_1175:
	s_mul_hi_i32 s4, s15, 0x2e8ba2e9
	s_lshr_b32 s12, s4, 31
	s_ashr_i32 s4, s4, 4
	s_add_i32 s12, s4, s12
	s_lshl_b32 s26, s12, 5
	v_or_b32_e32 v0, s26, v42
	v_ashrrev_i32_e32 v0, 2, v0
	s_mul_i32 s4, s12, 0xffffffa8
	v_lshl_or_b32 v1, v0, 13, v44
	v_lshl_add_u32 v2, v0, 5, v43
	v_cmp_gt_i32_e32 vcc, 8, v0
	s_add_i32 s4, s15, s4
	s_ashr_i32 s4, s4, 2
	v_cndmask_b32_e32 v0, v2, v1, vcc
	v_ashrrev_i32_e32 v1, 31, v0
	v_lshlrev_b64 v[0:1], 11, v[0:1]
	s_lshl_b32 s13, s4, 8
	s_and_b32 s12, s16, 0x60
	s_or_b32 s13, s13, s12
	v_lshl_add_u64 v[88:89], v[34:35], 0, v[0:1]
	v_or_b32_e32 v2, s13, v42
	v_ashrrev_i32_e32 v3, 31, v2
	v_lshlrev_b64 v[0:1], 11, v[2:3]
	v_lshl_add_u64 v[90:91], v[36:37], 0, v[0:1]
	v_add_co_u32_e32 v92, vcc, s20, v90
	v_or_b32_e32 v32, s26, v47
	s_nop 0
	v_addc_co_u32_e32 v93, vcc, 0, v91, vcc
	v_cmp_gt_i32_e32 vcc, 32, v32
	s_lshl_b32 s4, s4, 7
	s_or_b32 s4, s4, s12
	v_or_b32_e32 v76, s26, v50
	v_lshl_or_b32 v77, v32, 11, v48
	v_lshl_add_u32 v72, v32, 3, v57
	v_lshl_or_b32 v73, v76, 11, v51
	v_lshl_add_u32 v74, v76, 3, v57
	v_cndmask_b32_e32 v72, v72, v77, vcc
	v_cmp_gt_i32_e32 vcc, 32, v76
	s_nop 1
	v_cndmask_b32_e32 v74, v74, v73, vcc
	v_ashrrev_i32_e32 v73, 31, v72
	v_ashrrev_i32_e32 v75, 31, v74
	v_lshl_add_u64 v[68:69], v[72:73], 2, s[10:11]
	v_lshl_add_u64 v[70:71], v[74:75], 2, s[10:11]
	global_load_dwordx4 v[100:103], v[88:89], off
	global_load_dwordx4 v[104:107], v[88:89], off offset:32
	global_load_dwordx4 v[108:111], v[88:89], off offset:64
	global_load_dwordx4 v[112:115], v[88:89], off offset:96
	global_load_dwordx4 v[132:135], v[90:91], off
	global_load_dwordx4 v[136:139], v[90:91], off offset:32
	global_load_dwordx4 v[140:143], v[90:91], off offset:64
	global_load_dwordx4 v[144:147], v[90:91], off offset:96
	global_load_dwordx4 v[180:183], v[92:93], off
	global_load_dwordx4 v[184:187], v[92:93], off offset:32
	global_load_dwordx4 v[188:191], v[92:93], off offset:64
	global_load_dwordx4 v[192:195], v[92:93], off offset:96
	global_load_dwordx4 v[116:119], v[88:89], off offset:128
	global_load_dwordx4 v[120:123], v[88:89], off offset:160
	global_load_dwordx4 v[124:127], v[88:89], off offset:192
	global_load_dwordx4 v[128:131], v[88:89], off offset:224
	global_load_dwordx4 v[148:151], v[90:91], off offset:128
	global_load_dwordx4 v[152:155], v[90:91], off offset:160
	global_load_dwordx4 v[156:159], v[90:91], off offset:192
	global_load_dwordx4 v[160:163], v[90:91], off offset:224
	global_load_dwordx4 v[196:199], v[92:93], off offset:128
	global_load_dwordx4 v[200:203], v[92:93], off offset:160
	global_load_dwordx4 v[204:207], v[92:93], off offset:192
	global_load_dwordx4 v[208:211], v[92:93], off offset:224
	s_waitcnt vmcnt(19)
	v_mfma_f32_32x32x16_bf16 v[0:15], v[100:103], v[132:135], 0
	s_waitcnt vmcnt(15)
	v_mfma_f32_32x32x16_bf16 v[16:31], v[100:103], v[180:183], 0
	s_waitcnt vmcnt(18)
	v_mfma_f32_32x32x16_bf16 v[0:15], v[104:107], v[136:139], v[0:15]
	s_waitcnt vmcnt(14)
	v_mfma_f32_32x32x16_bf16 v[16:31], v[104:107], v[184:187], v[16:31]
	s_waitcnt vmcnt(17)
	v_mfma_f32_32x32x16_bf16 v[0:15], v[108:111], v[140:143], v[0:15]
	s_waitcnt vmcnt(13)
	v_mfma_f32_32x32x16_bf16 v[16:31], v[108:111], v[188:191], v[16:31]
	s_waitcnt vmcnt(16)
	v_mfma_f32_32x32x16_bf16 v[0:15], v[112:115], v[144:147], v[0:15]
	s_waitcnt vmcnt(12)
	v_mfma_f32_32x32x16_bf16 v[16:31], v[112:115], v[192:195], v[16:31]
	s_waitcnt vmcnt(7)
	v_mfma_f32_32x32x16_bf16 v[0:15], v[116:119], v[148:151], v[0:15]
	s_waitcnt vmcnt(3)
	v_mfma_f32_32x32x16_bf16 v[16:31], v[116:119], v[196:199], v[16:31]
	s_waitcnt vmcnt(6)
	v_mfma_f32_32x32x16_bf16 v[0:15], v[120:123], v[152:155], v[0:15]
	s_waitcnt vmcnt(2)
	v_mfma_f32_32x32x16_bf16 v[16:31], v[120:123], v[200:203], v[16:31]
	s_barrier
; __device__ __forceinline__ void up_fixup(const Args& a, LAS unsigned char* lds, int bx, int G, int tid, int wave, int lane) {
;     ...
;         for (int k = 0; k < 128; k += 16) { const bf16x8 af = *(const bf16x8*)(ap + k); ag = __builtin_amdgcn_mfma_f32_32x32x16_bf16(af, *(const bf16x8*)(bg + k), ag, 0, 0, 0); av = __builtin_amdgcn_mfma_f32_32x32x16_bf16(af, *(const bf16x8*)(bv + k), av, 0, 0, 0); }
;         __syncthreads();
; #pragma unroll
;         for (int i = 0; i < 16; ++i) { red[((wave * 2 + 0) * 16 + i) * 64 + lane] = ag[i]; red[((wave * 2 + 1) * 16 + i) * 64 + lane] = av[i]; }
;         __syncthreads();
; #pragma unroll
;         for (int h4 = 0; h4 < 4; ++h4) {
;             const int e = tid + h4 * 512, gv = e >> 10, i = (e >> 6) & 15, ln = e & 63;
;             float v = 0.f;
; #pragma unroll
;             for (int w = 0; w < 8; ++w) v += red[((w * 2 + gv) * 16 + i) * 64 + ln];
;             const int ml = (i & 3) + 8 * (i >> 2) + 4 * (ln >> 5);
;             tile[(gv * 32 + ml) * 32 + (ln & 31)] = v * rstd3[fix_row(mt * 32 + ml)];
;         }
;         __syncthreads();
;         {
;             const int q = tid >> 6, c = tid & 31, part = (tid >> 5) & 1, m0 = 4 * q, b = q;
;             const int j = 128 * pn + 32 * sub + c;
;             if (part == 0) {
;                 const float* cw = a.in[I_FCW]; const float* cb = a.in[I_FCB];
;                 const float ug0 = tile[(m0) * 32 + c], ug1 = tile[(m0 + 1) * 32 + c], uv0 = tile[(32 + m0) * 32 + c], uv1 = tile[(32 + m0 + 1) * 32 + c];
;                 float hg0 = 0.f, hg1 = 0.f, hv0 = 0.f, hv1 = 0.f;
;                 if (mt) { const float* ch = a.in[I_CFFN] + (size_t)(b * 2) * NUP; hg0 = ch[j]; hg1 = ch[NUP + j]; hv0 = ch[DFF + j]; hv1 = ch[NUP + DFF + j]; }
;                 const float wg0 = cw[j], wg1 = cw[NUP + j], wg2 = cw[2 * NUP + j], bgg = cb[j], wv0 = cw[DFF + j], wv1 = cw[NUP + DFF + j], wv2 = cw[2 * NUP + DFF + j], bvv = cb[DFF + j];
;                 const float cg0 = bgg + wg0 * hg0 + wg1 * hg1 + wg2 * ug0, cv0 = bvv + wv0 * hv0 + wv1 * hv1 + wv2 * uv0;
;                 const float cg1 = bgg + wg0 * hg1 + wg1 * ug0 + wg2 * ug1, cv1 = bvv + wv0 * hv1 + wv1 * uv0 + wv2 * uv1;
;                 bf16_t* act = (bf16_t*)(a.ws + WS_ACT);
;                 const int row0 = fix_row(mt * 32 + m0);
	s_waitcnt vmcnt(5)
	v_mfma_f32_32x32x16_bf16 v[0:15], v[124:127], v[156:159], v[0:15]
	s_waitcnt vmcnt(1)
	v_mfma_f32_32x32x16_bf16 v[16:31], v[124:127], v[204:207], v[16:31]
	s_waitcnt vmcnt(4)
	v_mfma_f32_32x32x16_bf16 v[0:15], v[128:131], v[160:163], v[0:15]
	s_waitcnt vmcnt(0)
	v_mfma_f32_32x32x16_bf16 v[16:31], v[128:131], v[208:211], v[16:31]
	s_nop 7
	ds_write2st64_b32 v58, v0, v1 offset1:1
	s_nop 2
	ds_write2st64_b32 v58, v16, v17 offset0:16 offset1:17
	ds_write2st64_b32 v58, v2, v3 offset0:2 offset1:3
	ds_write2st64_b32 v58, v18, v19 offset0:18 offset1:19
	ds_write2st64_b32 v58, v4, v5 offset0:4 offset1:5
	ds_write2st64_b32 v58, v20, v21 offset0:20 offset1:21
	ds_write2st64_b32 v58, v6, v7 offset0:6 offset1:7
	ds_write2st64_b32 v58, v22, v23 offset0:22 offset1:23
	ds_write2st64_b32 v58, v8, v9 offset0:8 offset1:9
	ds_write2st64_b32 v58, v24, v25 offset0:24 offset1:25
	ds_write2st64_b32 v58, v10, v11 offset0:10 offset1:11
	ds_write2st64_b32 v58, v26, v27 offset0:26 offset1:27
	ds_write2st64_b32 v58, v12, v13 offset0:12 offset1:13
	ds_write2st64_b32 v58, v28, v29 offset0:28 offset1:29
	ds_write2st64_b32 v58, v14, v15 offset0:14 offset1:15
	ds_write2st64_b32 v58, v30, v31 offset0:30 offset1:31
	s_waitcnt lgkmcnt(0)
	s_barrier
	global_load_dword v30, v[68:69], off
	global_load_dword v31, v[70:71], off
	v_or_b32_e32 v0, s26, v54
	v_lshl_or_b32 v1, v0, 11, v55
	v_lshl_add_u32 v2, v0, 3, v57
	v_cmp_gt_i32_e32 vcc, 32, v0
	s_nop 1
	v_cndmask_b32_e32 v0, v2, v1, vcc
	v_ashrrev_i32_e32 v1, 31, v0
	v_lshl_add_u64 v[0:1], v[0:1], 2, s[10:11]
	global_load_dword v32, v[0:1], off
	ds_read2st64_b32 v[0:1], v59 offset1:16
	ds_read2st64_b32 v[2:3], v59 offset0:32 offset1:48
	ds_read2st64_b32 v[4:5], v59 offset0:64 offset1:80
	ds_read2st64_b32 v[6:7], v59 offset0:96 offset1:112
	ds_read2st64_b32 v[8:9], v59 offset0:128 offset1:144
	ds_read2st64_b32 v[10:11], v59 offset0:160 offset1:176
	ds_read2st64_b32 v[12:13], v59 offset0:192 offset1:208
	ds_read2st64_b32 v[14:15], v59 offset0:224 offset1:240
	ds_read2st64_b32 v[16:17], v60 offset1:32
	ds_read2st64_b32 v[18:19], v60 offset0:64 offset1:96
	ds_read2st64_b32 v[20:21], v60 offset0:128 offset1:160
	ds_read2st64_b32 v[22:23], v60 offset0:192 offset1:224
	ds_read2st64_b32 v[24:25], v61 offset1:32
	ds_read2st64_b32 v[26:27], v61 offset0:64 offset1:96
	ds_read2st64_b32 v[28:29], v61 offset0:128 offset1:160
	s_waitcnt lgkmcnt(14)
	v_add_f32_e32 v0, 0, v0
	s_waitcnt lgkmcnt(6)
	v_add_f32_e32 v16, 0, v16
	v_add_f32_e32 v1, 0, v1
	v_add_f32_e32 v0, v0, v2
	v_add_f32_e32 v2, v16, v17
	v_add_f32_e32 v1, v1, v3
	v_add_f32_e32 v0, v0, v4
	s_waitcnt lgkmcnt(5)
	v_add_f32_e32 v2, v2, v18
	v_add_f32_e32 v1, v1, v5
	v_add_f32_e32 v0, v0, v6
	v_add_f32_e32 v2, v2, v19
	v_add_f32_e32 v1, v1, v7
	v_add_f32_e32 v0, v0, v8
	s_waitcnt lgkmcnt(4)
	v_add_f32_e32 v2, v2, v20
	v_add_f32_e32 v1, v1, v9
	v_add_f32_e32 v0, v0, v10
	v_add_f32_e32 v2, v2, v21
	v_add_f32_e32 v1, v1, v11
	v_add_f32_e32 v0, v0, v12
	s_waitcnt lgkmcnt(3)
	v_add_f32_e32 v2, v2, v22
	v_add_f32_e32 v1, v1, v13
	v_add_f32_e32 v0, v0, v14
	v_add_f32_e32 v2, v2, v23
	v_add_f32_e32 v1, v1, v15
	s_waitcnt lgkmcnt(2)
	v_add_f32_e32 v24, 0, v24
	v_add_f32_e32 v3, v24, v25
	s_waitcnt vmcnt(2)
	v_mul_f32_e32 v0, v0, v30
	s_waitcnt vmcnt(1)
	v_mul_f32_e32 v2, v2, v31
	v_mul_f32_e32 v1, v1, v30
	ds_write_b32 v49, v0
	ds_write_b32 v52, v2
	ds_write_b32 v53, v1
	ds_read2st64_b32 v[0:1], v61 offset0:192 offset1:224
	s_waitcnt lgkmcnt(5)
	v_add_f32_e32 v2, v3, v26
	v_add_f32_e32 v2, v2, v27
	s_waitcnt lgkmcnt(4)
	v_add_f32_e32 v2, v2, v28
	v_add_f32_e32 v2, v2, v29
	s_waitcnt lgkmcnt(0)
	v_add_f32_e32 v0, v2, v0
	v_add_f32_e32 v0, v0, v1
	s_waitcnt vmcnt(0)
	v_mul_f32_e32 v0, v0, v32
	v_or_b32_e32 v2, s4, v42
	ds_write_b32 v56, v0
	s_waitcnt lgkmcnt(0)
	s_barrier
	s_and_saveexec_b64 s[12:13], s[0:1]
	s_xor_b64 s[12:13], exec, s[12:13]
	s_cbranch_execz .LBB0_1177
	s_add_i32 s4, s15, 0x57
	s_cmpk_lt_u32 s4, 0xaf
	ds_read2_b32 v[0:1], v46 offset0:64 offset1:96
	s_cselect_b32 s4, s21, 0x105c8000
	v_lshl_add_u64 v[4:5], v[38:39], 0, s[4:5]
	v_ashrrev_i32_e32 v3, 31, v2
	v_lshl_add_u64 v[2:3], v[2:3], 2, v[4:5]
	v_add_co_u32_e32 v4, vcc, 0x5000, v2
	s_waitcnt lgkmcnt(0)
	global_store_dword v[2:3], v0, off
	v_addc_co_u32_e32 v5, vcc, 0, v3, vcc
	v_add_u32_e32 v0, 0x1000, v46
	global_store_dword v[4:5], v1, off offset:2048
	ds_read2_b32 v[0:1], v0 offset0:64 offset1:96
	v_add_co_u32_e32 v4, vcc, 0x2000, v2
	s_nop 1
	v_addc_co_u32_e32 v5, vcc, 0, v3, vcc
	v_add_co_u32_e32 v2, vcc, 0x8000, v2
	s_waitcnt lgkmcnt(0)
	global_store_dword v[4:5], v0, off offset:3072
	v_addc_co_u32_e32 v3, vcc, 0, v3, vcc
	global_store_dword v[2:3], v1, off offset:1024

; #define LAS __attribute__((address_space(3)))
; __device__ __forceinline__ unsigned f2bf(float f) { unsigned u = __float_as_uint(f); return (u + 0x7fffu + ((u >> 16) & 1u)) >> 16; }
; template <int MODE>
; __device__ __forceinline__ void mini_gemm(LAS unsigned char* lds, const bf16_t* A, const bf16_t* Bt, int K, int N, bf16_t* O, int ldc, const float* rstd, float* sumsq, int bx, int G, int tid, int wave, int lane) {
;     const int r = lane & 31, hf = lane >> 5, ntn = N >> 5, ntiles = 8 * ntn, kw = K >> 3;
;     LAS float* red = (LAS float*)lds;
;     for (int tile = bx; tile < ntiles; tile += G) {
;         const int m0 = (tile / ntn) * 32, n0 = (tile % ntn) * 32;
;         const bf16_t* ap = A + (size_t)(m0 + r) * K + wave * kw + 8 * hf; const bf16_t* bp = Bt + (size_t)(n0 + r) * K + wave * kw + 8 * hf;
;         f32x16 acc; for (int i = 0; i < 16; ++i) acc[i] = 0.f;
;         for (int k = 0; k < kw; k += 16) { const bf16x8 af = *(const bf16x8*)(ap + k), bf = *(const bf16x8*)(bp + k); acc = __builtin_amdgcn_mfma_f32_32x32x16_bf16(af, bf, acc, 0, 0, 0); }
;         __syncthreads();
; #pragma unroll
;         for (int i = 0; i < 16; ++i) red[(wave * 16 + i) * 64 + lane] = acc[i];
;         __syncthreads();
; #pragma unroll
;         for (int h2 = 0; h2 < 2; ++h2) {
;             const int e = tid + h2 * 512, i = e >> 6, ln = e & 63;
;             float v = 0.f;
; #pragma unroll
;             for (int w = 0; w < 8; ++w) v += red[(w * 16 + i) * 64 + ln];
;             const int row = m0 + (i & 3) + 8 * (i >> 2) + 4 * (ln >> 5), col = n0 + (ln & 31);
;             if (MODE == 0) { O[(size_t)row * ldc + col] = (bf16_t)f2bf(v * rstd[row]); }
;             else { O[(size_t)row * ldc + col] = (bf16_t)f2bf(v); float ss = v * v;
; #pragma unroll
;                 for (int o = 1; o < 32; o <<= 1) ss += __shfl_xor(ss, o);
;                 if ((ln & 31) == 0) atomicAdd(sumsq + row, ss); }
.LBB0_1296:
	s_ashr_i32 s0, s96, 31
	s_lshr_b32 s0, s0, 27
	s_add_i32 s0, s96, s0
	s_and_b32 s13, s0, 0xffffffe0
	v_or_b32_e32 v0, s13, v20
	s_ashr_i32 s12, s0, 5
	v_mad_i64_i32 v[54:55], s[0:1], v0, s10, v[16:17]
	s_mul_i32 s14, s12, 0xffd40000
	v_add_u32_e32 v4, s14, v32
	s_waitcnt lgkmcnt(0)
	v_ashrrev_i32_e32 v5, 31, v4
	v_lshl_add_u64 v[56:57], v[4:5], 1, v[18:19]
	s_lshl_b32 s0, s12, 10
	global_load_dwordx4 v[60:63], v[54:55], off
	global_load_dwordx4 v[64:67], v[54:55], off offset:32
	global_load_dwordx4 v[68:71], v[54:55], off offset:64
	global_load_dwordx4 v[72:75], v[54:55], off offset:96
	global_load_dwordx4 v[148:151], v[56:57], off
	global_load_dwordx4 v[152:155], v[56:57], off offset:32
	global_load_dwordx4 v[156:159], v[56:57], off offset:64
	global_load_dwordx4 v[160:163], v[56:57], off offset:96
	global_load_dwordx4 v[76:79], v[54:55], off offset:128
	global_load_dwordx4 v[80:83], v[54:55], off offset:160
	global_load_dwordx4 v[84:87], v[54:55], off offset:192
	global_load_dwordx4 v[88:91], v[54:55], off offset:224
	global_load_dwordx4 v[164:167], v[56:57], off offset:128
	global_load_dwordx4 v[168:171], v[56:57], off offset:160
	global_load_dwordx4 v[180:183], v[56:57], off offset:192
	global_load_dwordx4 v[184:187], v[56:57], off offset:224
	global_load_dwordx4 v[92:95], v[54:55], off offset:256
	global_load_dwordx4 v[96:99], v[54:55], off offset:288
	global_load_dwordx4 v[100:103], v[54:55], off offset:320
	global_load_dwordx4 v[104:107], v[54:55], off offset:352
	global_load_dwordx4 v[188:191], v[56:57], off offset:256
	global_load_dwordx4 v[192:195], v[56:57], off offset:288
	global_load_dwordx4 v[196:199], v[56:57], off offset:320
	global_load_dwordx4 v[200:203], v[56:57], off offset:352
	global_load_dwordx4 v[108:111], v[54:55], off offset:384
	global_load_dwordx4 v[112:115], v[54:55], off offset:416
	global_load_dwordx4 v[116:119], v[54:55], off offset:448
	global_load_dwordx4 v[120:123], v[54:55], off offset:480
	global_load_dwordx4 v[204:207], v[56:57], off offset:384
	global_load_dwordx4 v[208:211], v[56:57], off offset:416
	global_load_dwordx4 v[212:215], v[56:57], off offset:448
	global_load_dwordx4 v[216:219], v[56:57], off offset:480
	global_load_dwordx4 v[124:127], v[54:55], off offset:512
	global_load_dwordx4 v[128:131], v[54:55], off offset:544
	global_load_dwordx4 v[132:135], v[54:55], off offset:576
	global_load_dwordx4 v[136:139], v[54:55], off offset:608
	global_load_dwordx4 v[220:223], v[56:57], off offset:512
	global_load_dwordx4 v[224:227], v[56:57], off offset:544
	global_load_dwordx4 v[228:231], v[56:57], off offset:576
	global_load_dwordx4 v[232:235], v[56:57], off offset:608
	global_load_dwordx4 v[140:143], v[54:55], off offset:640
	global_load_dwordx4 v[144:147], v[54:55], off offset:672
	global_load_dwordx4 v[236:239], v[56:57], off offset:640
	global_load_dwordx4 v[240:243], v[56:57], off offset:672
	s_waitcnt vmcnt(39)
	v_mfma_f32_32x32x16_bf16 v[0:15], v[60:63], v[148:151], 0
	s_waitcnt vmcnt(38)
	v_mfma_f32_32x32x16_bf16 v[0:15], v[64:67], v[152:155], v[0:15]
	s_waitcnt vmcnt(37)
	v_mfma_f32_32x32x16_bf16 v[0:15], v[68:71], v[156:159], v[0:15]
	s_waitcnt vmcnt(36)
	v_mfma_f32_32x32x16_bf16 v[0:15], v[72:75], v[160:163], v[0:15]
	s_waitcnt vmcnt(31)
	v_mfma_f32_32x32x16_bf16 v[0:15], v[76:79], v[164:167], v[0:15]
	s_waitcnt vmcnt(30)
	v_mfma_f32_32x32x16_bf16 v[0:15], v[80:83], v[168:171], v[0:15]
	s_waitcnt vmcnt(29)
	v_mfma_f32_32x32x16_bf16 v[0:15], v[84:87], v[180:183], v[0:15]
	s_waitcnt vmcnt(28)
	v_mfma_f32_32x32x16_bf16 v[0:15], v[88:91], v[184:187], v[0:15]
	s_waitcnt vmcnt(23)
	v_mfma_f32_32x32x16_bf16 v[0:15], v[92:95], v[188:191], v[0:15]
	s_waitcnt vmcnt(22)
	v_mfma_f32_32x32x16_bf16 v[0:15], v[96:99], v[192:195], v[0:15]
	s_waitcnt vmcnt(21)
	v_mfma_f32_32x32x16_bf16 v[0:15], v[100:103], v[196:199], v[0:15]
	s_waitcnt vmcnt(20)
	v_mfma_f32_32x32x16_bf16 v[0:15], v[104:107], v[200:203], v[0:15]
	s_waitcnt vmcnt(15)
	v_mfma_f32_32x32x16_bf16 v[0:15], v[108:111], v[204:207], v[0:15]
	s_waitcnt vmcnt(14)
	v_mfma_f32_32x32x16_bf16 v[0:15], v[112:115], v[208:211], v[0:15]
	s_waitcnt vmcnt(13)
	v_mfma_f32_32x32x16_bf16 v[0:15], v[116:119], v[212:215], v[0:15]
	s_waitcnt vmcnt(12)
	v_mfma_f32_32x32x16_bf16 v[0:15], v[120:123], v[216:219], v[0:15]
	s_waitcnt vmcnt(7)
	v_mfma_f32_32x32x16_bf16 v[0:15], v[124:127], v[220:223], v[0:15]
	s_waitcnt vmcnt(6)
	v_mfma_f32_32x32x16_bf16 v[0:15], v[128:131], v[224:227], v[0:15]
	s_waitcnt vmcnt(5)
	v_mfma_f32_32x32x16_bf16 v[0:15], v[132:135], v[228:231], v[0:15]
	s_waitcnt vmcnt(4)
	v_mfma_f32_32x32x16_bf16 v[0:15], v[136:139], v[232:235], v[0:15]
	s_barrier
	s_waitcnt vmcnt(1)
	v_mfma_f32_32x32x16_bf16 v[0:15], v[140:143], v[236:239], v[0:15]
	s_waitcnt vmcnt(0)
	v_mfma_f32_32x32x16_bf16 v[0:15], v[144:147], v[240:243], v[0:15]
	s_nop 11
	ds_write2st64_b32 v33, v0, v1 offset1:1
	ds_write2st64_b32 v33, v2, v3 offset0:2 offset1:3
	ds_write2st64_b32 v33, v4, v5 offset0:4 offset1:5
	ds_write2st64_b32 v33, v6, v7 offset0:6 offset1:7
	ds_write2st64_b32 v33, v8, v9 offset0:8 offset1:9
	ds_write2st64_b32 v33, v10, v11 offset0:10 offset1:11
	ds_write2st64_b32 v33, v12, v13 offset0:12 offset1:13
	ds_write2st64_b32 v33, v14, v15 offset0:14 offset1:15
	s_waitcnt lgkmcnt(0)
	s_barrier
	ds_read2st64_b32 v[0:1], v22 offset1:16
	ds_read2st64_b32 v[2:3], v22 offset0:32 offset1:48
	ds_read2st64_b32 v[4:5], v22 offset0:64 offset1:80
	s_waitcnt lgkmcnt(2)
	v_add_f32_e32 v0, 0, v0
	v_add_f32_e32 v6, v0, v1
	ds_read2st64_b32 v[0:1], v22 offset0:96 offset1:112
	s_waitcnt lgkmcnt(2)
	v_add_f32_e32 v2, v6, v2
	v_add_f32_e32 v2, v2, v3
	s_waitcnt lgkmcnt(1)
	v_add_f32_e32 v2, v2, v4
	v_add_f32_e32 v2, v2, v5
	s_waitcnt lgkmcnt(0)
	v_add_f32_e32 v0, v2, v0
	v_add_f32_e32 v3, v0, v1
	v_mul_f32_e32 v0, v3, v3
	ds_bpermute_b32 v0, v24, v0
	v_or_b32_e32 v4, s13, v21
	v_bfe_u32 v7, v3, 16, 1
	v_add3_u32 v7, v3, v7, s11
	s_waitcnt lgkmcnt(0)
	v_fmac_f32_e32 v0, v3, v3
	ds_bpermute_b32 v1, v25, v0
	s_waitcnt lgkmcnt(0)
	v_add_f32_e32 v2, v0, v1
	ds_bpermute_b32 v5, v26, v2
	v_subrev_u32_e32 v0, s0, v31
	v_ashrrev_i32_e32 v1, 31, v0
	v_lshl_add_u64 v[0:1], v[0:1], 1, s[2:3]
	s_waitcnt lgkmcnt(0)
	v_add_f32_e32 v5, v2, v5
	ds_bpermute_b32 v6, v27, v5
	v_or_b32_e32 v2, v4, v23
	v_ashrrev_i32_e32 v3, 31, v2
	v_lshlrev_b64 v[8:9], 11, v[2:3]
	v_lshl_add_u64 v[8:9], v[0:1], 0, v[8:9]
	s_waitcnt lgkmcnt(0)
	v_add_f32_e32 v5, v5, v6
	ds_bpermute_b32 v6, v28, v5
	global_store_short_d16_hi v[8:9], v7, off
	s_and_saveexec_b64 s[0:1], vcc
	s_cbranch_execz .LBB0_1298
	v_lshl_add_u64 v[2:3], v[2:3], 2, s[4:5]
	s_waitcnt lgkmcnt(0)
	v_add_f32_e32 v5, v5, v6
	global_atomic_add_f32 v[2:3], v5, off
